# v24 + L2 warm-up loads of each 256-row ada_w chunk before its k loop (phase 0)
# baseline (speedup 1.0000x reference)
; __device__ void phase0_item(PP P, int wid, LAS unsigned char* lds, int item) {
;     ...
;         for (int kc = 0; kc < 4; ++kc) {
;             __syncthreads();
;             for (int e = tid; e < 40 * 256; e += NTHREADS) { const int b = e >> 8, k = kc * 256 + (e & 255);
;                 const float c = b < 32 ? P->in[2][b * D + k] : P->in[3][(b - 32) * D + k]; cs[e] = c / (1.f + __expf(-c)); }
;             __syncthreads();
;             for (int k = 0; k < 256; k += 4) {
;                 const float* wp = W + (size_t)(kc * 256 + k) * (6 * D) + col;
;                 const float w0 = wp[0], w1 = wp[6 * D], w2 = wp[2 * 6 * D], w3 = wp[3 * 6 * D];
.LBB0_64:
	s_andn2_b64 vcc, exec, s[4:5]
	s_cbranch_vccnz .LBB0_7
	s_load_dwordx2 s[6:7], s[16:17], 0x20
	v_cmp_gt_i32_e64 s[4:5], s84, v84
	v_lshl_add_u32 v110, v107, 2, s0
	s_waitcnt lgkmcnt(0)
	s_mov_b64 s[98:99], s[6:7]
	s_mul_i32 s8, s96, 0x556
	s_lshr_b32 s8, s8, 16
	s_mul_i32 s9, s8, 48
	s_sub_i32 s9, s96, s9
	s_mul_i32 s8, s8, 0x1800000
	s_lshl_b32 s9, s9, 9
	s_add_i32 s8, s8, s9
	v_lshrrev_b32_e32 v245, 5, v84
	v_and_b32_e32 v244, 31, v84
	v_mul_u32_u24_e32 v245, 0x6000, v245
	v_lshl_add_u32 v245, v244, 4, v245
	v_add_u32_e32 v245, s8, v245
	global_load_dwordx4 v[240:243], v245, s[98:99]
	v_add_u32_e32 v245, 0x60000, v245
	global_load_dwordx4 v[240:243], v245, s[98:99]
	v_add_u32_e32 v245, 0x60000, v245
	global_load_dwordx4 v[240:243], v245, s[98:99]
	v_add_u32_e32 v245, 0x60000, v245
	global_load_dwordx4 v[240:243], v245, s[98:99]
	v_add_u32_e32 v245, 0x60000, v245
	global_load_dwordx4 v[240:243], v245, s[98:99]
	v_add_u32_e32 v245, 0x60000, v245
	global_load_dwordx4 v[240:243], v245, s[98:99]
	v_add_u32_e32 v245, 0x60000, v245
	global_load_dwordx4 v[240:243], v245, s[98:99]
	v_add_u32_e32 v245, 0x60000, v245
	global_load_dwordx4 v[240:243], v245, s[98:99]
	v_add_u32_e32 v245, 0x60000, v245
	global_load_dwordx4 v[240:243], v245, s[98:99]
	v_add_u32_e32 v245, 0x60000, v245
	global_load_dwordx4 v[240:243], v245, s[98:99]
	v_add_u32_e32 v245, 0x60000, v245
	global_load_dwordx4 v[240:243], v245, s[98:99]
	v_add_u32_e32 v245, 0x60000, v245
	global_load_dwordx4 v[240:243], v245, s[98:99]
	v_add_u32_e32 v245, 0x60000, v245
	global_load_dwordx4 v[240:243], v245, s[98:99]
	v_add_u32_e32 v245, 0x60000, v245
	global_load_dwordx4 v[240:243], v245, s[98:99]
	v_add_u32_e32 v245, 0x60000, v245
	global_load_dwordx4 v[240:243], v245, s[98:99]
	v_add_u32_e32 v245, 0x60000, v245
	global_load_dwordx4 v[240:243], v245, s[98:99]
	v_add_u32_e32 v245, 0x60000, v245
	s_barrier
	s_and_saveexec_b64 s[8:9], s[4:5]
	s_cbranch_execz .LBB0_68
	v_lshl_add_u32 v2, v107, 2, s0
	s_mov_b64 s[10:11], 0
	v_mov_b32_e32 v3, v84

; #define LAS __attribute__((address_space(3)))
; __device__ void phase0_item(PP P, int wid, LAS unsigned char* lds, int item) {
;     ...
;             for (int k = 0; k < 256; k += 4) {
;                 const float* wp = W + (size_t)(kc * 256 + k) * (6 * D) + col;
;                 const float w0 = wp[0], w1 = wp[6 * D], w2 = wp[2 * 6 * D], w3 = wp[3 * 6 * D];
; #pragma unroll
;                 for (int i = 0; i < 10; ++i) { const f32x4 c4 = *(const LAS f32x4*)(cs + (bg * 10 + i) * 256 + k); acc[i] += c4[0] * w0 + c4[1] * w1 + c4[2] * w2 + c4[3] * w3; } }
.LBB0_69:
	v_add_co_u32_e32 v98, vcc, s86, v18
	s_mov_b32 s7, 0xfffd6000
	s_nop 0
	v_addc_co_u32_e32 v99, vcc, -1, v19, vcc
	v_add_co_u32_e32 v116, vcc, s87, v18
	s_mov_b32 s8, 0xfffdc000
	s_nop 0
	v_addc_co_u32_e32 v117, vcc, -1, v19, vcc
	v_add_co_u32_e32 v118, vcc, s88, v18
	s_mov_b32 s9, 0xfffe2000
	s_nop 0
	v_addc_co_u32_e32 v119, vcc, -1, v19, vcc
	v_add_co_u32_e32 v120, vcc, s7, v18
	s_mov_b32 s18, 0xfffe8000
	s_nop 0
	v_addc_co_u32_e32 v121, vcc, -1, v19, vcc
	v_add_co_u32_e32 v122, vcc, s8, v18
	ds_read_b128 v[2:5], v21
	ds_read_b128 v[6:9], v21 offset:16
	v_addc_co_u32_e32 v123, vcc, -1, v19, vcc
	v_add_co_u32_e32 v124, vcc, s9, v18
	global_load_dword v20, v[18:19], off
	s_nop 0
	v_addc_co_u32_e32 v125, vcc, -1, v19, vcc
	ds_read_b128 v[22:25], v21 offset:1024
	ds_read_b128 v[26:29], v21 offset:1040
	ds_read_b128 v[30:33], v21 offset:2048
	ds_read_b128 v[34:37], v21 offset:2064
	ds_read_b128 v[10:13], v21 offset:3072
	ds_read_b128 v[14:17], v21 offset:3088
	ds_read_b128 v[38:41], v21 offset:4096
	ds_read_b128 v[42:45], v21 offset:4112
	ds_read_b128 v[46:49], v21 offset:5120
	ds_read_b128 v[50:53], v21 offset:5136
	ds_read_b128 v[54:57], v21 offset:6144
	ds_read_b128 v[58:61], v21 offset:6160
	ds_read_b128 v[62:65], v21 offset:7168
	ds_read_b128 v[66:69], v21 offset:7184
	ds_read_b128 v[70:73], v21 offset:8192
	ds_read_b128 v[74:77], v21 offset:8208
	ds_read_b128 v[78:81], v21 offset:9216
	ds_read_b128 v[112:115], v21 offset:9232
	global_load_dword v82, v[116:117], off
	v_add_co_u32_e32 v116, vcc, s18, v18
	s_waitcnt lgkmcnt(14)
	v_mov_b32_e32 v127, v2
	v_addc_co_u32_e32 v117, vcc, -1, v19, vcc
	global_load_dword v118, v[118:119], off
	s_nop 0
	global_load_dword v122, v[122:123], off
	s_nop 0
	global_load_dword v98, v[98:99], off
	s_nop 0
	global_load_dword v124, v[124:125], off
	s_nop 0
	global_load_dword v116, v[116:117], off
	s_nop 0
	global_load_dword v120, v[120:121], off
	v_mov_b32_e32 v2, v23
	v_mov_b32_e32 v23, v4
	v_mov_b32_e32 v4, v25
	s_waitcnt lgkmcnt(13)
	v_mov_b32_e32 v25, v10
	v_mov_b32_e32 v10, v31
	v_mov_b32_e32 v31, v12
	v_mov_b32_e32 v12, v33
	s_waitcnt lgkmcnt(9)
	v_mov_b32_e32 v33, v46
	v_mov_b32_e32 v46, v39
	v_mov_b32_e32 v39, v48
	v_mov_b32_e32 v48, v41
	s_waitcnt lgkmcnt(5)
	v_mov_b32_e32 v41, v62
	v_mov_b32_e32 v62, v55
	v_mov_b32_e32 v55, v64
	v_mov_b32_e32 v64, v57
	s_waitcnt lgkmcnt(1)
	v_mov_b32_e32 v57, v78
	v_mov_b32_e32 v78, v71
	v_mov_b32_e32 v126, v22
	v_mov_b32_e32 v22, v24
	v_mov_b32_e32 v24, v30
	v_mov_b32_e32 v30, v32
	v_mov_b32_e32 v32, v38
	v_mov_b32_e32 v38, v40
	v_mov_b32_e32 v40, v54
	v_mov_b32_e32 v54, v56
	v_mov_b32_e32 v56, v70
	v_mov_b32_e32 v71, v80
	v_mov_b32_e32 v80, v73
	v_mov_b32_e32 v73, v6
	v_mov_b32_e32 v6, v27
	v_mov_b32_e32 v27, v8
	v_mov_b32_e32 v8, v29
	v_mov_b32_e32 v29, v14
	v_mov_b32_e32 v14, v35
	v_mov_b32_e32 v35, v16
	v_mov_b32_e32 v16, v37
	v_mov_b32_e32 v37, v50
	v_mov_b32_e32 v50, v43
	v_mov_b32_e32 v43, v52
	v_mov_b32_e32 v52, v45
	v_mov_b32_e32 v45, v66
	v_mov_b32_e32 v66, v59
	v_mov_b32_e32 v59, v68
	v_mov_b32_e32 v68, v61
	s_waitcnt lgkmcnt(0)
	v_mov_b32_e32 v61, v112
	v_mov_b32_e32 v112, v75
	v_mov_b32_e32 v70, v72
	v_mov_b32_e32 v72, v26
	v_mov_b32_e32 v26, v28
	v_mov_b32_e32 v28, v34
	v_mov_b32_e32 v34, v36
	v_mov_b32_e32 v36, v42
	v_mov_b32_e32 v42, v44
	v_mov_b32_e32 v44, v58
	v_mov_b32_e32 v58, v60
	v_mov_b32_e32 v60, v74
	v_mov_b32_e32 v74, v76
	v_mov_b32_e32 v75, v114
	v_mov_b32_e32 v114, v77
	v_add_u32_e32 v21, 32, v21
	s_add_i32 s6, s6, 8
	v_lshl_add_u64 v[18:19], v[18:19], 0, s[42:43]
	s_cmpk_gt_u32 s6, 0xfb
	s_waitcnt vmcnt(6)
	v_pk_mul_f32 v[6:7], v[82:83], v[6:7] op_sel_hi:[0,1]
	v_pk_mul_f32 v[14:15], v[82:83], v[14:15] op_sel_hi:[0,1]
	s_waitcnt vmcnt(4)
	v_pk_mul_f32 v[2:3], v[122:123], v[2:3] op_sel_hi:[0,1]
	v_pk_mul_f32 v[10:11], v[122:123], v[10:11] op_sel_hi:[0,1]
	v_pk_mul_f32 v[46:47], v[122:123], v[46:47] op_sel_hi:[0,1]
	v_pk_mul_f32 v[62:63], v[122:123], v[62:63] op_sel_hi:[0,1]
	v_pk_mul_f32 v[78:79], v[122:123], v[78:79] op_sel_hi:[0,1]
	v_pk_mul_f32 v[50:51], v[82:83], v[50:51] op_sel_hi:[0,1]
	v_pk_mul_f32 v[66:67], v[82:83], v[66:67] op_sel_hi:[0,1]
	v_pk_mul_f32 v[76:77], v[82:83], v[112:113] op_sel_hi:[0,1]
	s_waitcnt vmcnt(0)
	v_pk_fma_f32 v[2:3], v[120:121], v[126:127], v[2:3] op_sel_hi:[0,1,1]
	v_pk_fma_f32 v[10:11], v[120:121], v[24:25], v[10:11] op_sel_hi:[0,1,1]
	v_pk_fma_f32 v[24:25], v[120:121], v[32:33], v[46:47] op_sel_hi:[0,1,1]
	v_pk_fma_f32 v[32:33], v[120:121], v[40:41], v[62:63] op_sel_hi:[0,1,1]
	v_pk_fma_f32 v[40:41], v[120:121], v[56:57], v[78:79] op_sel_hi:[0,1,1]
	v_pk_fma_f32 v[6:7], v[98:99], v[72:73], v[6:7] op_sel_hi:[0,1,1]
	v_pk_fma_f32 v[14:15], v[98:99], v[28:29], v[14:15] op_sel_hi:[0,1,1]
	v_pk_fma_f32 v[28:29], v[98:99], v[36:37], v[50:51] op_sel_hi:[0,1,1]
	v_pk_fma_f32 v[36:37], v[98:99], v[44:45], v[66:67] op_sel_hi:[0,1,1]
	v_pk_fma_f32 v[44:45], v[98:99], v[60:61], v[76:77] op_sel_hi:[0,1,1]
	v_pk_fma_f32 v[2:3], v[124:125], v[22:23], v[2:3] op_sel_hi:[0,1,1]
	v_pk_fma_f32 v[10:11], v[124:125], v[30:31], v[10:11] op_sel_hi:[0,1,1]
	v_pk_fma_f32 v[22:23], v[124:125], v[38:39], v[24:25] op_sel_hi:[0,1,1]
	v_pk_fma_f32 v[24:25], v[124:125], v[54:55], v[32:33] op_sel_hi:[0,1,1]
	v_pk_fma_f32 v[30:31], v[124:125], v[70:71], v[40:41] op_sel_hi:[0,1,1]
	v_pk_fma_f32 v[6:7], v[118:119], v[26:27], v[6:7] op_sel_hi:[0,1,1]
	v_pk_fma_f32 v[14:15], v[118:119], v[34:35], v[14:15] op_sel_hi:[0,1,1]
	v_pk_fma_f32 v[26:27], v[118:119], v[42:43], v[28:29] op_sel_hi:[0,1,1]
	v_pk_fma_f32 v[28:29], v[118:119], v[58:59], v[36:37] op_sel_hi:[0,1,1]
	v_pk_fma_f32 v[34:35], v[118:119], v[74:75], v[44:45] op_sel_hi:[0,1,1]
	v_pk_fma_f32 v[2:3], v[116:117], v[4:5], v[2:3] op_sel_hi:[0,1,1]
	v_pk_fma_f32 v[4:5], v[116:117], v[12:13], v[10:11] op_sel_hi:[0,1,1]
	v_pk_fma_f32 v[10:11], v[116:117], v[48:49], v[22:23] op_sel_hi:[0,1,1]
	v_pk_fma_f32 v[12:13], v[116:117], v[64:65], v[24:25] op_sel_hi:[0,1,1]
	v_pk_fma_f32 v[22:23], v[116:117], v[80:81], v[30:31] op_sel_hi:[0,1,1]
	v_pk_fma_f32 v[6:7], v[20:21], v[8:9], v[6:7] op_sel_hi:[0,1,1]
	v_pk_fma_f32 v[8:9], v[20:21], v[16:17], v[14:15] op_sel_hi:[0,1,1]
	v_pk_fma_f32 v[14:15], v[20:21], v[52:53], v[26:27] op_sel_hi:[0,1,1]
	v_pk_fma_f32 v[16:17], v[20:21], v[68:69], v[28:29] op_sel_hi:[0,1,1]
	v_pk_fma_f32 v[26:27], v[20:21], v[114:115], v[34:35] op_sel_hi:[0,1,1]
	v_pk_add_f32 v[2:3], v[86:87], v[2:3]
	v_pk_add_f32 v[4:5], v[88:89], v[4:5]
	v_pk_add_f32 v[10:11], v[90:91], v[10:11]
	v_pk_add_f32 v[12:13], v[92:93], v[12:13]
	v_pk_add_f32 v[22:23], v[94:95], v[22:23]
	v_pk_add_f32 v[86:87], v[2:3], v[6:7]
	v_pk_add_f32 v[88:89], v[4:5], v[8:9]
	v_pk_add_f32 v[90:91], v[10:11], v[14:15]
	v_pk_add_f32 v[92:93], v[12:13], v[16:17]
	v_pk_add_f32 v[94:95], v[22:23], v[26:27]
	s_cbranch_scc0 .LBB0_69
; __device__ void phase0_item(PP P, int wid, LAS unsigned char* lds, int item) {
;     ...
;         for (int kc = 0; kc < 4; ++kc) {
;             __syncthreads();
;             for (int e = tid; e < 40 * 256; e += NTHREADS) { const int b = e >> 8, k = kc * 256 + (e & 255);
;                 const float c = b < 32 ? P->in[2][b * D + k] : P->in[3][(b - 32) * D + k]; cs[e] = c / (1.f + __expf(-c)); }
;             __syncthreads();
;             for (int k = 0; k < 256; k += 4) {
;                 const float* wp = W + (size_t)(kc * 256 + k) * (6 * D) + col;
;                 const float w0 = wp[0], w1 = wp[6 * D], w2 = wp[2 * 6 * D], w3 = wp[3 * 6 * D];
	global_load_dwordx4 v[240:243], v245, s[98:99]
	v_add_u32_e32 v245, 0x60000, v245
	global_load_dwordx4 v[240:243], v245, s[98:99]
	v_add_u32_e32 v245, 0x60000, v245
	global_load_dwordx4 v[240:243], v245, s[98:99]
	v_add_u32_e32 v245, 0x60000, v245
	global_load_dwordx4 v[240:243], v245, s[98:99]
	v_add_u32_e32 v245, 0x60000, v245
	global_load_dwordx4 v[240:243], v245, s[98:99]
	v_add_u32_e32 v245, 0x60000, v245
	global_load_dwordx4 v[240:243], v245, s[98:99]
	v_add_u32_e32 v245, 0x60000, v245
	global_load_dwordx4 v[240:243], v245, s[98:99]
	v_add_u32_e32 v245, 0x60000, v245
	global_load_dwordx4 v[240:243], v245, s[98:99]
	v_add_u32_e32 v245, 0x60000, v245
	global_load_dwordx4 v[240:243], v245, s[98:99]
	v_add_u32_e32 v245, 0x60000, v245
	global_load_dwordx4 v[240:243], v245, s[98:99]
	v_add_u32_e32 v245, 0x60000, v245
	global_load_dwordx4 v[240:243], v245, s[98:99]
	v_add_u32_e32 v245, 0x60000, v245
	global_load_dwordx4 v[240:243], v245, s[98:99]
	v_add_u32_e32 v245, 0x60000, v245
	global_load_dwordx4 v[240:243], v245, s[98:99]
	v_add_u32_e32 v245, 0x60000, v245
	global_load_dwordx4 v[240:243], v245, s[98:99]
	v_add_u32_e32 v245, 0x60000, v245
	global_load_dwordx4 v[240:243], v245, s[98:99]
	v_add_u32_e32 v245, 0x60000, v245
	global_load_dwordx4 v[240:243], v245, s[98:99]
	v_add_u32_e32 v245, 0x60000, v245
	s_barrier
	s_and_saveexec_b64 s[6:7], s[4:5]
	s_cbranch_execz .LBB0_73
	v_lshl_add_u32 v2, v107, 2, s0
	s_mov_b64 s[8:9], 0
	v_mov_b32_e32 v3, v84

; #define LAS __attribute__((address_space(3)))
; __device__ void phase0_item(PP P, int wid, LAS unsigned char* lds, int item) {
;     ...
;             for (int k = 0; k < 256; k += 4) {
;                 const float* wp = W + (size_t)(kc * 256 + k) * (6 * D) + col;
;                 const float w0 = wp[0], w1 = wp[6 * D], w2 = wp[2 * 6 * D], w3 = wp[3 * 6 * D];
; #pragma unroll
;                 for (int i = 0; i < 10; ++i) { const f32x4 c4 = *(const LAS f32x4*)(cs + (bg * 10 + i) * 256 + k); acc[i] += c4[0] * w0 + c4[1] * w1 + c4[2] * w2 + c4[3] * w3; } }
.LBB0_74:
	v_add_co_u32_e32 v112, vcc, 0xfffd6000, v98
	s_mov_b64 s[6:7], vcc
	v_add_co_u32_e32 v116, vcc, s86, v98
	ds_read_b128 v[2:5], v82
	ds_read_b128 v[6:9], v82 offset:16
	ds_read_b128 v[10:13], v82 offset:1024
	ds_read_b128 v[30:33], v82 offset:1040
	ds_read_b128 v[42:45], v82 offset:2048
	ds_read_b128 v[38:41], v82 offset:2064
	ds_read_b128 v[14:17], v82 offset:3072
	ds_read_b128 v[18:21], v82 offset:3088
	ds_read_b128 v[58:61], v82 offset:4096
	ds_read_b128 v[50:53], v82 offset:4112
	ds_read_b128 v[22:25], v82 offset:5120
	ds_read_b128 v[26:29], v82 offset:5136
	ds_read_b128 v[70:73], v82 offset:6144
	ds_read_b128 v[66:69], v82 offset:6160
	ds_read_b128 v[34:37], v82 offset:7168
	ds_read_b128 v[46:49], v82 offset:7184
	ds_read_b128 v[78:81], v82 offset:8192
	ds_read_b128 v[74:77], v82 offset:8208
	ds_read_b128 v[54:57], v82 offset:9216
	ds_read_b128 v[62:65], v82 offset:9232
	v_addc_co_u32_e32 v117, vcc, -1, v99, vcc
	v_add_co_u32_e32 v118, vcc, s87, v98
	global_load_dword v114, v[98:99], off
	s_nop 0
	v_addc_co_u32_e32 v119, vcc, -1, v99, vcc
	v_add_co_u32_e32 v120, vcc, s88, v98
	s_waitcnt lgkmcnt(14)
	v_mov_b32_e32 v128, v10
	v_addc_co_u32_e32 v121, vcc, -1, v99, vcc
	v_add_co_u32_e32 v122, vcc, 0xfffdc000, v98
	s_mov_b64 s[8:9], vcc
	v_addc_co_u32_e64 v113, vcc, -1, v99, s[6:7]
	v_add_co_u32_e32 v124, vcc, 0xfffe2000, v98
	global_load_dword v118, v[118:119], off
	s_nop 0
	global_load_dword v120, v[120:121], off
	s_nop 0
	global_load_dword v116, v[116:117], off
	s_mov_b64 s[6:7], vcc
	v_addc_co_u32_e64 v123, vcc, -1, v99, s[8:9]
	global_load_dword v112, v[112:113], off
	s_nop 0
	global_load_dword v122, v[122:123], off
	v_add_co_u32_e32 v126, vcc, 0xfffe8000, v98
	v_addc_co_u32_e64 v125, s[6:7], -1, v99, s[6:7]
	global_load_dword v124, v[124:125], off
	v_addc_co_u32_e32 v127, vcc, -1, v99, vcc
	v_mov_b32_e32 v10, v12
	v_mov_b32_e32 v12, v42
	v_mov_b32_e32 v42, v44
	s_waitcnt lgkmcnt(11)
	v_mov_b32_e32 v44, v58
	v_mov_b32_e32 v58, v60
	global_load_dword v60, v[126:127], off
	s_waitcnt lgkmcnt(5)
	v_mov_b32_e32 v127, v34
	v_mov_b32_e32 v34, v71
	v_mov_b32_e32 v71, v36
	v_mov_b32_e32 v36, v73
	s_waitcnt lgkmcnt(1)
	v_mov_b32_e32 v73, v54
	v_mov_b32_e32 v54, v79
	v_mov_b32_e32 v79, v56
	v_mov_b32_e32 v56, v81
	v_mov_b32_e32 v81, v6
	v_mov_b32_e32 v6, v31
	v_mov_b32_e32 v31, v8
	v_mov_b32_e32 v8, v33
	v_mov_b32_e32 v33, v18
	v_mov_b32_e32 v18, v39
	v_mov_b32_e32 v39, v20
	v_mov_b32_e32 v20, v41
	v_mov_b32_e32 v41, v26
	v_mov_b32_e32 v26, v51
	v_mov_b32_e32 v51, v28
	v_mov_b32_e32 v28, v53
	v_mov_b32_e32 v53, v46
	v_mov_b32_e32 v46, v67
	v_mov_b32_e32 v129, v2
	v_mov_b32_e32 v2, v11
	v_mov_b32_e32 v11, v4
	v_mov_b32_e32 v4, v13
	v_mov_b32_e32 v13, v14
	v_mov_b32_e32 v14, v43
	v_mov_b32_e32 v43, v16
	v_mov_b32_e32 v16, v45
	v_mov_b32_e32 v45, v22
	v_mov_b32_e32 v22, v59
	v_mov_b32_e32 v126, v70
	v_mov_b32_e32 v70, v72
	v_mov_b32_e32 v72, v78
	v_mov_b32_e32 v78, v80
	v_mov_b32_e32 v80, v30
	v_mov_b32_e32 v30, v32
	v_mov_b32_e32 v32, v38
	v_mov_b32_e32 v38, v40
	v_mov_b32_e32 v40, v50
	v_mov_b32_e32 v50, v52
	v_mov_b32_e32 v52, v66
	v_mov_b32_e32 v67, v48
	v_mov_b32_e32 v48, v69
	s_waitcnt lgkmcnt(0)
	v_mov_b32_e32 v69, v62
	v_mov_b32_e32 v62, v75
	v_mov_b32_e32 v59, v24
	v_mov_b32_e32 v66, v68
	v_mov_b32_e32 v68, v74
	v_mov_b32_e32 v24, v61
	v_mov_b32_e32 v74, v76
	v_mov_b32_e32 v75, v64
	v_mov_b32_e32 v64, v77
	s_add_i32 s18, s18, 8
	v_add_u32_e32 v82, 32, v82
	s_cmpk_lt_u32 s18, 0xfc
	v_lshl_add_u64 v[98:99], v[98:99], 0, s[42:43]
	s_waitcnt vmcnt(6)
	v_pk_mul_f32 v[18:19], v[118:119], v[18:19] op_sel_hi:[0,1]
	v_pk_mul_f32 v[46:47], v[118:119], v[46:47] op_sel_hi:[0,1]
	s_waitcnt vmcnt(4)
	v_pk_fma_f32 v[18:19], v[116:117], v[32:33], v[18:19] op_sel_hi:[0,1,1]
	v_pk_fma_f32 v[32:33], v[116:117], v[52:53], v[46:47] op_sel_hi:[0,1,1]
	v_pk_mul_f32 v[6:7], v[118:119], v[6:7] op_sel_hi:[0,1]
	v_pk_mul_f32 v[26:27], v[118:119], v[26:27] op_sel_hi:[0,1]
	s_waitcnt vmcnt(2)
	v_pk_mul_f32 v[2:3], v[122:123], v[2:3] op_sel_hi:[0,1]
	v_pk_mul_f32 v[14:15], v[122:123], v[14:15] op_sel_hi:[0,1]
	v_pk_mul_f32 v[22:23], v[122:123], v[22:23] op_sel_hi:[0,1]
	v_pk_mul_f32 v[34:35], v[122:123], v[34:35] op_sel_hi:[0,1]
	v_pk_mul_f32 v[46:47], v[122:123], v[54:55] op_sel_hi:[0,1]
	v_pk_mul_f32 v[62:63], v[118:119], v[62:63] op_sel_hi:[0,1]
	v_pk_fma_f32 v[2:3], v[112:113], v[128:129], v[2:3] op_sel_hi:[0,1,1]
	v_pk_fma_f32 v[12:13], v[112:113], v[12:13], v[14:15] op_sel_hi:[0,1,1]
	v_pk_fma_f32 v[14:15], v[112:113], v[44:45], v[22:23] op_sel_hi:[0,1,1]
	v_pk_fma_f32 v[22:23], v[112:113], v[126:127], v[34:35] op_sel_hi:[0,1,1]
	v_pk_fma_f32 v[34:35], v[112:113], v[72:73], v[46:47] op_sel_hi:[0,1,1]
	v_pk_fma_f32 v[6:7], v[116:117], v[80:81], v[6:7] op_sel_hi:[0,1,1]
	v_pk_fma_f32 v[26:27], v[116:117], v[40:41], v[26:27] op_sel_hi:[0,1,1]
	v_pk_fma_f32 v[40:41], v[116:117], v[68:69], v[62:63] op_sel_hi:[0,1,1]
	s_waitcnt vmcnt(1)
	v_pk_fma_f32 v[2:3], v[124:125], v[10:11], v[2:3] op_sel_hi:[0,1,1]
	v_pk_fma_f32 v[10:11], v[124:125], v[42:43], v[12:13] op_sel_hi:[0,1,1]
	v_pk_fma_f32 v[12:13], v[124:125], v[58:59], v[14:15] op_sel_hi:[0,1,1]
	v_pk_fma_f32 v[14:15], v[124:125], v[70:71], v[22:23] op_sel_hi:[0,1,1]
	v_pk_fma_f32 v[22:23], v[124:125], v[78:79], v[34:35] op_sel_hi:[0,1,1]
	v_pk_fma_f32 v[6:7], v[120:121], v[30:31], v[6:7] op_sel_hi:[0,1,1]
	v_pk_fma_f32 v[18:19], v[120:121], v[38:39], v[18:19] op_sel_hi:[0,1,1]
	v_pk_fma_f32 v[26:27], v[120:121], v[50:51], v[26:27] op_sel_hi:[0,1,1]
	v_pk_fma_f32 v[30:31], v[120:121], v[66:67], v[32:33] op_sel_hi:[0,1,1]
	v_pk_fma_f32 v[32:33], v[120:121], v[74:75], v[40:41] op_sel_hi:[0,1,1]
	s_waitcnt vmcnt(0)
	v_pk_fma_f32 v[2:3], v[60:61], v[4:5], v[2:3] op_sel_hi:[0,1,1]
	v_pk_fma_f32 v[4:5], v[60:61], v[16:17], v[10:11] op_sel_hi:[0,1,1]
	v_pk_fma_f32 v[10:11], v[60:61], v[24:25], v[12:13] op_sel_hi:[0,1,1]
	v_pk_fma_f32 v[12:13], v[60:61], v[36:37], v[14:15] op_sel_hi:[0,1,1]
	v_pk_fma_f32 v[14:15], v[60:61], v[56:57], v[22:23] op_sel_hi:[0,1,1]
	v_pk_fma_f32 v[6:7], v[114:115], v[8:9], v[6:7] op_sel_hi:[0,1,1]
	v_pk_fma_f32 v[8:9], v[114:115], v[20:21], v[18:19] op_sel_hi:[0,1,1]
	v_pk_fma_f32 v[18:19], v[114:115], v[28:29], v[26:27] op_sel_hi:[0,1,1]
	v_pk_fma_f32 v[20:21], v[114:115], v[48:49], v[30:31] op_sel_hi:[0,1,1]
	v_pk_fma_f32 v[26:27], v[114:115], v[64:65], v[32:33] op_sel_hi:[0,1,1]
	v_pk_add_f32 v[2:3], v[86:87], v[2:3]
	v_pk_add_f32 v[4:5], v[88:89], v[4:5]
	v_pk_add_f32 v[10:11], v[90:91], v[10:11]
	v_pk_add_f32 v[12:13], v[92:93], v[12:13]
	v_pk_add_f32 v[14:15], v[94:95], v[14:15]
	v_pk_add_f32 v[86:87], v[2:3], v[6:7]
	v_pk_add_f32 v[88:89], v[4:5], v[8:9]
	v_pk_add_f32 v[90:91], v[10:11], v[18:19]
	v_pk_add_f32 v[92:93], v[12:13], v[20:21]
	v_pk_add_f32 v[94:95], v[14:15], v[26:27]
	s_cbranch_scc1 .LBB0_74
; __device__ void phase0_item(PP P, int wid, LAS unsigned char* lds, int item) {
;     ...
;         for (int kc = 0; kc < 4; ++kc) {
;             __syncthreads();
;             for (int e = tid; e < 40 * 256; e += NTHREADS) { const int b = e >> 8, k = kc * 256 + (e & 255);
;                 const float c = b < 32 ? P->in[2][b * D + k] : P->in[3][(b - 32) * D + k]; cs[e] = c / (1.f + __expf(-c)); }
;             __syncthreads();
;             for (int k = 0; k < 256; k += 4) {
;                 const float* wp = W + (size_t)(kc * 256 + k) * (6 * D) + col;
;                 const float w0 = wp[0], w1 = wp[6 * D], w2 = wp[2 * 6 * D], w3 = wp[3 * 6 * D];
	global_load_dwordx4 v[240:243], v245, s[98:99]
	v_add_u32_e32 v245, 0x60000, v245
	global_load_dwordx4 v[240:243], v245, s[98:99]
	v_add_u32_e32 v245, 0x60000, v245
	global_load_dwordx4 v[240:243], v245, s[98:99]
	v_add_u32_e32 v245, 0x60000, v245
	global_load_dwordx4 v[240:243], v245, s[98:99]
	v_add_u32_e32 v245, 0x60000, v245
	global_load_dwordx4 v[240:243], v245, s[98:99]
	v_add_u32_e32 v245, 0x60000, v245
	global_load_dwordx4 v[240:243], v245, s[98:99]
	v_add_u32_e32 v245, 0x60000, v245
	global_load_dwordx4 v[240:243], v245, s[98:99]
	v_add_u32_e32 v245, 0x60000, v245
	global_load_dwordx4 v[240:243], v245, s[98:99]
	v_add_u32_e32 v245, 0x60000, v245
	global_load_dwordx4 v[240:243], v245, s[98:99]
	v_add_u32_e32 v245, 0x60000, v245
	global_load_dwordx4 v[240:243], v245, s[98:99]
	v_add_u32_e32 v245, 0x60000, v245
	global_load_dwordx4 v[240:243], v245, s[98:99]
	v_add_u32_e32 v245, 0x60000, v245
	global_load_dwordx4 v[240:243], v245, s[98:99]
	v_add_u32_e32 v245, 0x60000, v245
	global_load_dwordx4 v[240:243], v245, s[98:99]
	v_add_u32_e32 v245, 0x60000, v245
	global_load_dwordx4 v[240:243], v245, s[98:99]
	v_add_u32_e32 v245, 0x60000, v245
	global_load_dwordx4 v[240:243], v245, s[98:99]
	v_add_u32_e32 v245, 0x60000, v245
	global_load_dwordx4 v[240:243], v245, s[98:99]
	v_add_u32_e32 v245, 0x60000, v245
	s_barrier
	s_and_saveexec_b64 s[6:7], s[4:5]
	s_cbranch_execz .LBB0_78
	v_lshl_add_u32 v2, v107, 2, s0
	s_mov_b64 s[8:9], 0
	v_mov_b32_e32 v3, v84

; #define LAS __attribute__((address_space(3)))
; __device__ void phase0_item(PP P, int wid, LAS unsigned char* lds, int item) {
;     ...
;             for (int k = 0; k < 256; k += 4) {
;                 const float* wp = W + (size_t)(kc * 256 + k) * (6 * D) + col;
;                 const float w0 = wp[0], w1 = wp[6 * D], w2 = wp[2 * 6 * D], w3 = wp[3 * 6 * D];
; #pragma unroll
;                 for (int i = 0; i < 10; ++i) { const f32x4 c4 = *(const LAS f32x4*)(cs + (bg * 10 + i) * 256 + k); acc[i] += c4[0] * w0 + c4[1] * w1 + c4[2] * w2 + c4[3] * w3; } }
.LBB0_79:
	v_add_co_u32_e32 v32, vcc, 0xfffd6000, v30
	s_mov_b64 s[6:7], vcc
	v_add_co_u32_e32 v80, vcc, s86, v30
	ds_read_b128 v[2:5], v35
	ds_read_b128 v[6:9], v35 offset:16
	v_addc_co_u32_e32 v81, vcc, -1, v31, vcc
	v_add_co_u32_e32 v98, vcc, s87, v30
	global_load_dword v34, v[30:31], off
	s_nop 0
	v_addc_co_u32_e32 v99, vcc, -1, v31, vcc
	v_add_co_u32_e32 v120, vcc, s88, v30
	ds_read_b128 v[36:39], v35 offset:1024
	ds_read_b128 v[40:43], v35 offset:1040
	ds_read_b128 v[44:47], v35 offset:2048
	ds_read_b128 v[48:51], v35 offset:2064
	ds_read_b128 v[10:13], v35 offset:3072
	ds_read_b128 v[14:17], v35 offset:3088
	ds_read_b128 v[52:55], v35 offset:4096
	ds_read_b128 v[56:59], v35 offset:4112
	ds_read_b128 v[18:21], v35 offset:5120
	ds_read_b128 v[22:25], v35 offset:5136
	ds_read_b128 v[60:63], v35 offset:6144
	ds_read_b128 v[64:67], v35 offset:6160
	ds_read_b128 v[26:29], v35 offset:7168
	ds_read_b128 v[68:71], v35 offset:7184
	ds_read_b128 v[72:75], v35 offset:8192
	ds_read_b128 v[76:79], v35 offset:8208
	ds_read_b128 v[112:115], v35 offset:9216
	ds_read_b128 v[116:119], v35 offset:9232
	v_addc_co_u32_e32 v121, vcc, -1, v31, vcc
	v_add_co_u32_e32 v122, vcc, 0xfffdc000, v30
	s_mov_b64 s[8:9], vcc
	v_addc_co_u32_e64 v33, vcc, -1, v31, s[6:7]
	global_load_dword v82, v[98:99], off
	s_nop 0
	global_load_dword v98, v[120:121], off
	s_nop 0
	global_load_dword v80, v[80:81], off
	v_add_co_u32_e32 v120, vcc, 0xfffe2000, v30
	s_mov_b64 s[6:7], vcc
	v_addc_co_u32_e64 v123, vcc, -1, v31, s[8:9]
	global_load_dword v32, v[32:33], off
	s_nop 0
	global_load_dword v122, v[122:123], off
	v_add_co_u32_e32 v124, vcc, 0xfffe8000, v30
	v_addc_co_u32_e64 v121, s[6:7], -1, v31, s[6:7]
	global_load_dword v120, v[120:121], off
	v_addc_co_u32_e32 v125, vcc, -1, v31, vcc
	s_waitcnt lgkmcnt(14)
	v_mov_b32_e32 v126, v36
	v_mov_b32_e32 v36, v38
	v_mov_b32_e32 v38, v44
	v_mov_b32_e32 v44, v46
	s_waitcnt lgkmcnt(11)
	v_mov_b32_e32 v46, v52
	v_mov_b32_e32 v52, v54
	global_load_dword v54, v[124:125], off
	s_waitcnt lgkmcnt(5)
	v_mov_b32_e32 v125, v26
	v_mov_b32_e32 v26, v61
	v_mov_b32_e32 v61, v28
	v_mov_b32_e32 v28, v63
	s_waitcnt lgkmcnt(1)
	v_mov_b32_e32 v63, v112
	v_mov_b32_e32 v112, v73
	v_mov_b32_e32 v73, v114
	v_mov_b32_e32 v114, v75
	v_mov_b32_e32 v75, v6
	v_mov_b32_e32 v6, v41
	v_mov_b32_e32 v41, v8
	v_mov_b32_e32 v8, v43
	v_mov_b32_e32 v43, v14
	v_mov_b32_e32 v14, v49
	v_mov_b32_e32 v49, v16
	v_mov_b32_e32 v16, v51
	v_mov_b32_e32 v51, v22
	v_mov_b32_e32 v22, v57
	v_mov_b32_e32 v57, v24
	v_mov_b32_e32 v24, v59
	v_mov_b32_e32 v59, v68
	v_mov_b32_e32 v68, v65
	v_mov_b32_e32 v127, v2
	v_mov_b32_e32 v2, v37
	v_mov_b32_e32 v37, v4
	v_mov_b32_e32 v4, v39
	v_mov_b32_e32 v39, v10
	v_mov_b32_e32 v10, v45
	v_mov_b32_e32 v45, v12
	v_mov_b32_e32 v12, v47
	v_mov_b32_e32 v47, v18
	v_mov_b32_e32 v18, v53
	v_mov_b32_e32 v124, v60
	v_mov_b32_e32 v60, v62
	v_mov_b32_e32 v62, v72
	v_mov_b32_e32 v72, v74
	v_mov_b32_e32 v74, v40
	v_mov_b32_e32 v40, v42
	v_mov_b32_e32 v42, v48
	v_mov_b32_e32 v48, v50
	v_mov_b32_e32 v50, v56
	v_mov_b32_e32 v56, v58
	v_mov_b32_e32 v58, v64
	v_mov_b32_e32 v65, v70
	v_mov_b32_e32 v70, v67
	s_waitcnt lgkmcnt(0)
	v_mov_b32_e32 v67, v116
	v_mov_b32_e32 v116, v77
	v_add_u32_e32 v35, 32, v35
	v_mov_b32_e32 v53, v20
	v_mov_b32_e32 v64, v66
	v_mov_b32_e32 v66, v76
	v_mov_b32_e32 v76, v78
	v_mov_b32_e32 v77, v118
	v_mov_b32_e32 v118, v79
	v_mov_b32_e32 v20, v55
	s_add_i32 s18, s18, 8
	s_cmpk_lt_u32 s18, 0xfc
	s_waitcnt vmcnt(6)
	v_pk_mul_f32 v[6:7], v[82:83], v[6:7] op_sel_hi:[0,1]
	v_pk_mul_f32 v[14:15], v[82:83], v[14:15] op_sel_hi:[0,1]
	v_pk_mul_f32 v[22:23], v[82:83], v[22:23] op_sel_hi:[0,1]
	v_pk_mul_f32 v[68:69], v[82:83], v[68:69] op_sel_hi:[0,1]
	s_waitcnt vmcnt(4)
	v_pk_fma_f32 v[6:7], v[80:81], v[74:75], v[6:7] op_sel_hi:[0,1,1]
	v_pk_fma_f32 v[14:15], v[80:81], v[42:43], v[14:15] op_sel_hi:[0,1,1]
	v_pk_fma_f32 v[22:23], v[80:81], v[50:51], v[22:23] op_sel_hi:[0,1,1]
	v_pk_fma_f32 v[42:43], v[80:81], v[58:59], v[68:69] op_sel_hi:[0,1,1]
	s_waitcnt vmcnt(2)
	v_pk_mul_f32 v[2:3], v[122:123], v[2:3] op_sel_hi:[0,1]
	v_pk_mul_f32 v[10:11], v[122:123], v[10:11] op_sel_hi:[0,1]
	v_pk_mul_f32 v[18:19], v[122:123], v[18:19] op_sel_hi:[0,1]
	v_pk_mul_f32 v[26:27], v[122:123], v[26:27] op_sel_hi:[0,1]
	v_pk_mul_f32 v[58:59], v[122:123], v[112:113] op_sel_hi:[0,1]
	v_pk_mul_f32 v[78:79], v[82:83], v[116:117] op_sel_hi:[0,1]
	v_pk_fma_f32 v[6:7], v[98:99], v[40:41], v[6:7] op_sel_hi:[0,1,1]
	v_pk_fma_f32 v[14:15], v[98:99], v[48:49], v[14:15] op_sel_hi:[0,1,1]
	v_pk_fma_f32 v[22:23], v[98:99], v[56:57], v[22:23] op_sel_hi:[0,1,1]
	v_pk_fma_f32 v[2:3], v[32:33], v[126:127], v[2:3] op_sel_hi:[0,1,1]
	v_pk_fma_f32 v[10:11], v[32:33], v[38:39], v[10:11] op_sel_hi:[0,1,1]
	v_pk_fma_f32 v[18:19], v[32:33], v[46:47], v[18:19] op_sel_hi:[0,1,1]
	v_pk_fma_f32 v[26:27], v[32:33], v[124:125], v[26:27] op_sel_hi:[0,1,1]
	v_pk_fma_f32 v[32:33], v[32:33], v[62:63], v[58:59] op_sel_hi:[0,1,1]
	v_pk_fma_f32 v[50:51], v[80:81], v[66:67], v[78:79] op_sel_hi:[0,1,1]
	v_pk_fma_f32 v[6:7], v[34:35], v[8:9], v[6:7] op_sel_hi:[0,1,1]
	v_pk_fma_f32 v[8:9], v[34:35], v[16:17], v[14:15] op_sel_hi:[0,1,1]
	v_pk_fma_f32 v[14:15], v[34:35], v[24:25], v[22:23] op_sel_hi:[0,1,1]
	s_waitcnt vmcnt(1)
	v_pk_fma_f32 v[2:3], v[120:121], v[36:37], v[2:3] op_sel_hi:[0,1,1]
	v_pk_fma_f32 v[10:11], v[120:121], v[44:45], v[10:11] op_sel_hi:[0,1,1]
	v_pk_fma_f32 v[18:19], v[120:121], v[52:53], v[18:19] op_sel_hi:[0,1,1]
	v_pk_fma_f32 v[24:25], v[120:121], v[60:61], v[26:27] op_sel_hi:[0,1,1]
	v_pk_fma_f32 v[26:27], v[120:121], v[72:73], v[32:33] op_sel_hi:[0,1,1]
	v_pk_fma_f32 v[40:41], v[98:99], v[64:65], v[42:43] op_sel_hi:[0,1,1]
	v_pk_fma_f32 v[42:43], v[98:99], v[76:77], v[50:51] op_sel_hi:[0,1,1]
	s_waitcnt vmcnt(0)
	v_pk_fma_f32 v[2:3], v[54:55], v[4:5], v[2:3] op_sel_hi:[0,1,1]
	v_pk_fma_f32 v[4:5], v[54:55], v[12:13], v[10:11] op_sel_hi:[0,1,1]
	v_pk_fma_f32 v[10:11], v[54:55], v[20:21], v[18:19] op_sel_hi:[0,1,1]
	v_pk_fma_f32 v[12:13], v[54:55], v[28:29], v[24:25] op_sel_hi:[0,1,1]
	v_pk_fma_f32 v[18:19], v[54:55], v[114:115], v[26:27] op_sel_hi:[0,1,1]
	v_pk_fma_f32 v[16:17], v[34:35], v[70:71], v[40:41] op_sel_hi:[0,1,1]
	v_pk_fma_f32 v[22:23], v[34:35], v[118:119], v[42:43] op_sel_hi:[0,1,1]
	v_pk_add_f32 v[2:3], v[86:87], v[2:3]
	v_pk_add_f32 v[4:5], v[88:89], v[4:5]
	v_pk_add_f32 v[10:11], v[90:91], v[10:11]
	v_pk_add_f32 v[12:13], v[92:93], v[12:13]
	v_pk_add_f32 v[18:19], v[94:95], v[18:19]
	v_lshl_add_u64 v[30:31], v[30:31], 0, s[42:43]
	v_pk_add_f32 v[86:87], v[2:3], v[6:7]
	v_pk_add_f32 v[88:89], v[4:5], v[8:9]
	v_pk_add_f32 v[90:91], v[10:11], v[14:15]
	v_pk_add_f32 v[92:93], v[12:13], v[16:17]
	v_pk_add_f32 v[94:95], v[18:19], v[22:23]
	s_cbranch_scc1 .LBB0_79
; __device__ void phase0_item(PP P, int wid, LAS unsigned char* lds, int item) {
;     ...
;         for (int kc = 0; kc < 4; ++kc) {
;             __syncthreads();
;             for (int e = tid; e < 40 * 256; e += NTHREADS) { const int b = e >> 8, k = kc * 256 + (e & 255);
;                 const float c = b < 32 ? P->in[2][b * D + k] : P->in[3][(b - 32) * D + k]; cs[e] = c / (1.f + __expf(-c)); }
;             __syncthreads();
;             for (int k = 0; k < 256; k += 4) {
;                 const float* wp = W + (size_t)(kc * 256 + k) * (6 * D) + col;
;                 const float w0 = wp[0], w1 = wp[6 * D], w2 = wp[2 * 6 * D], w3 = wp[3 * 6 * D];
	global_load_dwordx4 v[240:243], v245, s[98:99]
	v_add_u32_e32 v245, 0x60000, v245
	global_load_dwordx4 v[240:243], v245, s[98:99]
	v_add_u32_e32 v245, 0x60000, v245
	global_load_dwordx4 v[240:243], v245, s[98:99]
	v_add_u32_e32 v245, 0x60000, v245
	global_load_dwordx4 v[240:243], v245, s[98:99]
	v_add_u32_e32 v245, 0x60000, v245
	global_load_dwordx4 v[240:243], v245, s[98:99]
	v_add_u32_e32 v245, 0x60000, v245
	global_load_dwordx4 v[240:243], v245, s[98:99]
	v_add_u32_e32 v245, 0x60000, v245
	global_load_dwordx4 v[240:243], v245, s[98:99]
	v_add_u32_e32 v245, 0x60000, v245
	global_load_dwordx4 v[240:243], v245, s[98:99]
	v_add_u32_e32 v245, 0x60000, v245
	global_load_dwordx4 v[240:243], v245, s[98:99]
	v_add_u32_e32 v245, 0x60000, v245
	global_load_dwordx4 v[240:243], v245, s[98:99]
	v_add_u32_e32 v245, 0x60000, v245
	global_load_dwordx4 v[240:243], v245, s[98:99]
	v_add_u32_e32 v245, 0x60000, v245
	global_load_dwordx4 v[240:243], v245, s[98:99]
	v_add_u32_e32 v245, 0x60000, v245
	global_load_dwordx4 v[240:243], v245, s[98:99]
	v_add_u32_e32 v245, 0x60000, v245
	global_load_dwordx4 v[240:243], v245, s[98:99]
	v_add_u32_e32 v245, 0x60000, v245
	global_load_dwordx4 v[240:243], v245, s[98:99]
	v_add_u32_e32 v245, 0x60000, v245
	global_load_dwordx4 v[240:243], v245, s[98:99]
	v_add_u32_e32 v245, 0x60000, v245
	s_barrier
	s_and_saveexec_b64 s[6:7], s[4:5]
	s_cbranch_execz .LBB0_83
	s_mov_b64 s[4:5], 0
